# v15 + non-temporal (nt) cache hint on the coalesced bf16 epilogue stores of the in-proj (Z) and mlp1 (U1) GEMMs
# baseline (speedup 1.0000x reference)
; DI unsigned pk2(float lo, float hi) { f32x2 v = {lo, hi}; bf2_t r = __builtin_convertvector(v, bf2_t); return __builtin_bit_cast(unsigned, r); }
;     DI void operator()(const f32x4 (&acc)[2][2][4][2], const Unit& u, int wr, int wc, int fr, int fq) const {
;         const int row0 = u.pm * BM + wr * 64 + fr, col0 = u.pn * BM + wc * 32 + 8 * fq;
; #pragma unroll
;         for (int ai = 0; ai < 2; ++ai)
; #pragma unroll
;             for (int m = 0; m < 4; ++m) { const size_t row = (size_t)(row0 + ai * HALF + m * 16);
; #pragma unroll
;                 for (int bj = 0; bj < 2; ++bj) { const int col = col0 + bj * HALF; const f32x4 v0 = acc[ai][bj][m][0], v1 = acc[ai][bj][m][1];
;                     u32x4 w; w.x = pk2(v0[0], v0[1]); w.y = pk2(v0[2], v0[3]); w.z = pk2(v1[0], v1[1]); w.w = pk2(v1[2], v1[3]);
;                     *(u32x4*)(Z + row * ZW + col) = w;
.LBB0_158:
	s_lshl_b32 s74, s25, 8
	v_readlane_b32 s75, v253, 17
	s_or_b32 s74, s74, s75
	s_cmpk_eq_u32 s74, 0x700
	s_cbranch_scc1 .Lepi_ip_orig
	s_cmpk_eq_u32 s74, 0xb20
	s_cbranch_scc1 .Lepi_ip_orig
	v_mbcnt_lo_u32_b32 v156, -1, 0
	v_mbcnt_hi_u32_b32 v156, -1, v156
	v_readlane_b32 s74, v253, 14
	v_readlane_b32 s76, v253, 12
	v_readlane_b32 s77, v253, 13
	v_and_b32_e32 v157, 15, v156
	v_lshrrev_b32_e32 v158, 4, v156
	v_bfe_u32 v159, v156, 2, 2
	v_xor_b32_e32 v159, v159, v158
	v_lshlrev_b32_e32 v159, 4, v159
	v_lshl_or_b32 v157, v157, 6, v159
	v_and_b32_e32 v159, 3, v156
	v_xor_b32_e32 v158, v158, v159
	v_lshlrev_b32_e32 v158, 4, v158
	v_lshrrev_b32_e32 v156, 2, v156
	v_lshl_or_b32 v158, v156, 6, v158
	s_add_i32 s75, s74, 0xc000
	v_add_u32_e32 v157, s75, v157
	v_add_u32_e32 v158, s75, v158
	v_lshlrev_b32_e32 v159, 4, v159
	v_mov_b32_e32 v160, 0x1800
	v_mad_u32_u24 v159, v156, v160, v159
	s_lshr_b32 s74, s74, 10
	s_lshr_b32 s75, s74, 2
	s_and_b32 s74, s74, 3
	s_mul_i32 s75, s75, 0x60000
	s_lshl_b32 s74, s74, 6
	s_add_i32 s75, s75, s74
	v_add_u32_e32 v159, s75, v159
	s_mul_i32 s75, s26, 0x180000
	s_lshl_b32 s74, s25, 9
	s_add_u32 s75, s75, s74
	s_add_u32 s76, s76, s75
	s_addc_u32 s77, s77, 0
	v_cvt_pk_bf16_f32 v160, v126, v127
	v_cvt_pk_bf16_f32 v161, v128, v129
	v_cvt_pk_bf16_f32 v162, v122, v123
	v_cvt_pk_bf16_f32 v163, v124, v125
	ds_write_b128 v157, v[160:163]
	ds_read_b128 v[168:171], v158
	v_cvt_pk_bf16_f32 v164, v118, v119
	v_cvt_pk_bf16_f32 v165, v120, v121
	v_cvt_pk_bf16_f32 v166, v114, v115
	v_cvt_pk_bf16_f32 v167, v116, v117
	ds_write_b128 v157, v[164:167] offset:8192
	ds_read_b128 v[172:175], v158 offset:8192
	s_waitcnt lgkmcnt(2)
	global_store_dwordx4 v159, v[168:171], s[76:77] nt
	v_cvt_pk_bf16_f32 v160, v108, v109
	v_cvt_pk_bf16_f32 v161, v110, v111
	v_cvt_pk_bf16_f32 v162, v104, v105
	v_cvt_pk_bf16_f32 v163, v106, v107
	ds_write_b128 v157, v[160:163]
	ds_read_b128 v[176:179], v158
	s_waitcnt lgkmcnt(2)
	global_store_dwordx4 v159, v[172:175], s[76:77] offset:256 nt
	v_cvt_pk_bf16_f32 v164, v100, v101
	v_cvt_pk_bf16_f32 v165, v102, v103
	v_cvt_pk_bf16_f32 v166, v96, v97
	v_cvt_pk_bf16_f32 v167, v98, v99
	ds_write_b128 v157, v[164:167] offset:8192
	ds_read_b128 v[180:183], v158 offset:8192
	s_waitcnt lgkmcnt(2)
	s_add_u32 s76, s76, 0x18000
	s_addc_u32 s77, s77, 0
	global_store_dwordx4 v159, v[176:179], s[76:77] nt
	v_cvt_pk_bf16_f32 v160, v92, v93
	v_cvt_pk_bf16_f32 v161, v94, v95
	v_cvt_pk_bf16_f32 v162, v88, v89
	v_cvt_pk_bf16_f32 v163, v90, v91
	ds_write_b128 v157, v[160:163]
	ds_read_b128 v[168:171], v158
	s_waitcnt lgkmcnt(2)
	global_store_dwordx4 v159, v[180:183], s[76:77] offset:256 nt
	v_cvt_pk_bf16_f32 v164, v84, v85
	v_cvt_pk_bf16_f32 v165, v86, v87
	v_cvt_pk_bf16_f32 v166, v80, v81
	v_cvt_pk_bf16_f32 v167, v82, v83
	ds_write_b128 v157, v[164:167] offset:8192
	ds_read_b128 v[172:175], v158 offset:8192
	s_waitcnt lgkmcnt(2)
	s_add_u32 s76, s76, 0x18000
	s_addc_u32 s77, s77, 0
	global_store_dwordx4 v159, v[168:171], s[76:77] nt
	v_cvt_pk_bf16_f32 v160, v76, v77
	v_cvt_pk_bf16_f32 v161, v78, v79
	v_cvt_pk_bf16_f32 v162, v72, v73
	v_cvt_pk_bf16_f32 v163, v74, v75
	ds_write_b128 v157, v[160:163]
	ds_read_b128 v[176:179], v158
	s_waitcnt lgkmcnt(2)
	global_store_dwordx4 v159, v[172:175], s[76:77] offset:256 nt
	v_cvt_pk_bf16_f32 v164, v68, v69
	v_cvt_pk_bf16_f32 v165, v70, v71
	v_cvt_pk_bf16_f32 v166, v64, v65
	v_cvt_pk_bf16_f32 v167, v66, v67
	ds_write_b128 v157, v[164:167] offset:8192
	ds_read_b128 v[180:183], v158 offset:8192
	s_waitcnt lgkmcnt(2)
	s_add_u32 s76, s76, 0x18000
	s_addc_u32 s77, s77, 0
	global_store_dwordx4 v159, v[176:179], s[76:77] nt
	v_cvt_pk_bf16_f32 v160, v60, v61
	v_cvt_pk_bf16_f32 v161, v62, v63
	v_cvt_pk_bf16_f32 v162, v56, v57
	v_cvt_pk_bf16_f32 v163, v58, v59
	ds_write_b128 v157, v[160:163]
	ds_read_b128 v[168:171], v158
	s_waitcnt lgkmcnt(2)
	global_store_dwordx4 v159, v[180:183], s[76:77] offset:256 nt
	v_cvt_pk_bf16_f32 v164, v52, v53
	v_cvt_pk_bf16_f32 v165, v54, v55
	v_cvt_pk_bf16_f32 v166, v48, v49
	v_cvt_pk_bf16_f32 v167, v50, v51
	ds_write_b128 v157, v[164:167] offset:8192
	ds_read_b128 v[172:175], v158 offset:8192
	s_waitcnt lgkmcnt(2)
	s_add_u32 s76, s76, 0x78000
	s_addc_u32 s77, s77, 0
	global_store_dwordx4 v159, v[168:171], s[76:77] nt
	v_cvt_pk_bf16_f32 v160, v44, v45
	v_cvt_pk_bf16_f32 v161, v46, v47
	v_cvt_pk_bf16_f32 v162, v40, v41
	v_cvt_pk_bf16_f32 v163, v42, v43
	ds_write_b128 v157, v[160:163]
	ds_read_b128 v[176:179], v158
	s_waitcnt lgkmcnt(2)
	global_store_dwordx4 v159, v[172:175], s[76:77] offset:256 nt
	v_cvt_pk_bf16_f32 v164, v36, v37
	v_cvt_pk_bf16_f32 v165, v38, v39
	v_cvt_pk_bf16_f32 v166, v32, v33
	v_cvt_pk_bf16_f32 v167, v34, v35
	ds_write_b128 v157, v[164:167] offset:8192
	ds_read_b128 v[180:183], v158 offset:8192
	s_waitcnt lgkmcnt(2)
	s_add_u32 s76, s76, 0x18000
	s_addc_u32 s77, s77, 0
	global_store_dwordx4 v159, v[176:179], s[76:77] nt
	v_cvt_pk_bf16_f32 v160, v28, v29
	v_cvt_pk_bf16_f32 v161, v30, v31
	v_cvt_pk_bf16_f32 v162, v24, v25
	v_cvt_pk_bf16_f32 v163, v26, v27
	ds_write_b128 v157, v[160:163]
	ds_read_b128 v[168:171], v158
	s_waitcnt lgkmcnt(2)
	global_store_dwordx4 v159, v[180:183], s[76:77] offset:256 nt
	v_cvt_pk_bf16_f32 v164, v20, v21
	v_cvt_pk_bf16_f32 v165, v22, v23
	v_cvt_pk_bf16_f32 v166, v16, v17
	v_cvt_pk_bf16_f32 v167, v18, v19
	ds_write_b128 v157, v[164:167] offset:8192
	ds_read_b128 v[172:175], v158 offset:8192
	s_waitcnt lgkmcnt(2)
	s_add_u32 s76, s76, 0x18000
	s_addc_u32 s77, s77, 0
	global_store_dwordx4 v159, v[168:171], s[76:77] nt
	v_cvt_pk_bf16_f32 v160, v12, v13
	v_cvt_pk_bf16_f32 v161, v14, v15
	v_cvt_pk_bf16_f32 v162, v8, v9
	v_cvt_pk_bf16_f32 v163, v10, v11
	ds_write_b128 v157, v[160:163]
	ds_read_b128 v[176:179], v158
	s_waitcnt lgkmcnt(2)
	global_store_dwordx4 v159, v[172:175], s[76:77] offset:256 nt
	v_cvt_pk_bf16_f32 v164, v4, v5
	v_cvt_pk_bf16_f32 v165, v6, v7
	v_cvt_pk_bf16_f32 v166, v0, v1
	v_cvt_pk_bf16_f32 v167, v2, v3
	ds_write_b128 v157, v[164:167] offset:8192
	ds_read_b128 v[180:183], v158 offset:8192
	s_waitcnt lgkmcnt(2)
	s_add_u32 s76, s76, 0x18000
	s_addc_u32 s77, s77, 0
	global_store_dwordx4 v159, v[176:179], s[76:77] nt
	s_waitcnt lgkmcnt(0)
	global_store_dwordx4 v159, v[180:183], s[76:77] offset:256 nt
	s_movk_i32 s36, 0x44
	s_andn2_b64 vcc, exec, s[0:1]
	s_mov_b64 s[0:1], -1
	s_cbranch_vccnz .LBB0_151
	s_branch .Lepi_ip_after
	s_nop 0

; DI unsigned pk2(float lo, float hi) { f32x2 v = {lo, hi}; bf2_t r = __builtin_convertvector(v, bf2_t); return __builtin_bit_cast(unsigned, r); }
;     DI void operator()(const f32x4 (&acc)[2][2][4][2], const Unit& u, int wr, int wc, int fr, int fq) const {
;     ...
;             for (int m = 0; m < 4; ++m) { const size_t row = (size_t)(row0 + ai * HALF + m * 16);
; #pragma unroll
;                 for (int bj = 0; bj < 2; ++bj) { const int col = col0 + bj * HALF; f32x4 v0 = acc[ai][bj][m][0], v1 = acc[ai][bj][m][1];
; #pragma unroll
;                     for (int j = 0; j < 4; ++j) { const float a = fmaxf(v0[j], 0.f), b = fmaxf(v1[j], 0.f); v0[j] = a * a; v1[j] = b * b; }
;                     u32x4 w; w.x = pk2(v0[0], v0[1]); w.y = pk2(v0[2], v0[3]); w.z = pk2(v1[0], v1[1]); w.w = pk2(v1[2], v1[3]);
;                     *(u32x4*)(U + row * FF + col) = w; } }
.LBB0_911:
	v_mbcnt_lo_u32_b32 v144, -1, 0
	v_mbcnt_hi_u32_b32 v144, -1, v144
	v_readlane_b32 s3, v253, 14
	v_readlane_b32 s16, v253, 12
	v_readlane_b32 s17, v253, 13
	v_and_b32_e32 v145, 15, v144
	v_lshrrev_b32_e32 v146, 4, v144
	v_bfe_u32 v147, v144, 2, 2
	v_xor_b32_e32 v147, v147, v146
	v_lshlrev_b32_e32 v147, 4, v147
	v_lshl_or_b32 v145, v145, 6, v147
	v_and_b32_e32 v147, 3, v144
	v_xor_b32_e32 v146, v146, v147
	v_lshlrev_b32_e32 v146, 4, v146
	v_lshrrev_b32_e32 v144, 2, v144
	v_lshl_or_b32 v146, v144, 6, v146
	s_add_i32 s18, s3, 0xc000
	v_add_u32_e32 v145, s18, v145
	v_add_u32_e32 v146, s18, v146
	v_lshlrev_b32_e32 v147, 4, v147
	v_lshl_or_b32 v147, v144, 13, v147
	s_lshr_b32 s3, s3, 10
	s_lshr_b32 s18, s3, 2
	s_and_b32 s3, s3, 3
	s_lshl_b32 s18, s18, 19
	s_lshl_b32 s3, s3, 6
	s_add_i32 s18, s18, s3
	v_add_u32_e32 v147, s18, v147
	s_lshl_b32 s18, s14, 21
	s_lshl_b32 s3, s35, 9
	s_add_u32 s18, s18, s3
	s_add_u32 s16, s16, s18
	s_addc_u32 s17, s17, 0
	v_max_f32_e32 v126, 0, v126
	v_max_f32_e32 v127, 0, v127
	v_max_f32_e32 v128, 0, v128
	v_max_f32_e32 v129, 0, v129
	v_max_f32_e32 v122, 0, v122
	v_max_f32_e32 v123, 0, v123
	v_max_f32_e32 v124, 0, v124
	v_max_f32_e32 v125, 0, v125
	v_pk_mul_f32 v[126:127], v[126:127], v[126:127]
	v_pk_mul_f32 v[128:129], v[128:129], v[128:129]
	v_pk_mul_f32 v[122:123], v[122:123], v[122:123]
	v_pk_mul_f32 v[124:125], v[124:125], v[124:125]
	v_cvt_pk_bf16_f32 v152, v126, v127
	v_cvt_pk_bf16_f32 v153, v128, v129
	v_cvt_pk_bf16_f32 v154, v122, v123
	v_cvt_pk_bf16_f32 v155, v124, v125
	ds_write_b128 v145, v[152:155]
	ds_read_b128 v[160:163], v146
	v_max_f32_e32 v118, 0, v118
	v_max_f32_e32 v119, 0, v119
	v_max_f32_e32 v120, 0, v120
	v_max_f32_e32 v121, 0, v121
	v_max_f32_e32 v114, 0, v114
	v_max_f32_e32 v115, 0, v115
	v_max_f32_e32 v116, 0, v116
	v_max_f32_e32 v117, 0, v117
	v_pk_mul_f32 v[118:119], v[118:119], v[118:119]
	v_pk_mul_f32 v[120:121], v[120:121], v[120:121]
	v_pk_mul_f32 v[114:115], v[114:115], v[114:115]
	v_pk_mul_f32 v[116:117], v[116:117], v[116:117]
	v_cvt_pk_bf16_f32 v156, v118, v119
	v_cvt_pk_bf16_f32 v157, v120, v121
	v_cvt_pk_bf16_f32 v158, v114, v115
	v_cvt_pk_bf16_f32 v159, v116, v117
	ds_write_b128 v145, v[156:159] offset:8192
	ds_read_b128 v[164:167], v146 offset:8192
	s_waitcnt lgkmcnt(2)
	global_store_dwordx4 v147, v[160:163], s[16:17] nt
	v_max_f32_e32 v108, 0, v108
	v_max_f32_e32 v109, 0, v109
	v_max_f32_e32 v110, 0, v110
	v_max_f32_e32 v111, 0, v111
	v_max_f32_e32 v104, 0, v104
	v_max_f32_e32 v105, 0, v105
	v_max_f32_e32 v106, 0, v106
	v_max_f32_e32 v107, 0, v107
	v_pk_mul_f32 v[108:109], v[108:109], v[108:109]
	v_pk_mul_f32 v[110:111], v[110:111], v[110:111]
	v_pk_mul_f32 v[104:105], v[104:105], v[104:105]
	v_pk_mul_f32 v[106:107], v[106:107], v[106:107]
	v_cvt_pk_bf16_f32 v152, v108, v109
	v_cvt_pk_bf16_f32 v153, v110, v111
	v_cvt_pk_bf16_f32 v154, v104, v105
	v_cvt_pk_bf16_f32 v155, v106, v107
	ds_write_b128 v145, v[152:155]
	ds_read_b128 v[168:171], v146
	s_waitcnt lgkmcnt(2)
	global_store_dwordx4 v147, v[164:167], s[16:17] offset:256 nt
	v_max_f32_e32 v100, 0, v100
	v_max_f32_e32 v101, 0, v101
	v_max_f32_e32 v102, 0, v102
	v_max_f32_e32 v103, 0, v103
	v_max_f32_e32 v96, 0, v96
	v_max_f32_e32 v97, 0, v97
	v_max_f32_e32 v98, 0, v98
	v_max_f32_e32 v99, 0, v99
	v_pk_mul_f32 v[100:101], v[100:101], v[100:101]
	v_pk_mul_f32 v[102:103], v[102:103], v[102:103]
	v_pk_mul_f32 v[96:97], v[96:97], v[96:97]
	v_pk_mul_f32 v[98:99], v[98:99], v[98:99]
	v_cvt_pk_bf16_f32 v156, v100, v101
	v_cvt_pk_bf16_f32 v157, v102, v103
	v_cvt_pk_bf16_f32 v158, v96, v97
	v_cvt_pk_bf16_f32 v159, v98, v99
	ds_write_b128 v145, v[156:159] offset:8192
	ds_read_b128 v[172:175], v146 offset:8192
	s_waitcnt lgkmcnt(2)
	s_add_u32 s16, s16, 0x20000
	s_addc_u32 s17, s17, 0
	global_store_dwordx4 v147, v[168:171], s[16:17] nt
	v_max_f32_e32 v92, 0, v92
	v_max_f32_e32 v93, 0, v93
	v_max_f32_e32 v94, 0, v94
	v_max_f32_e32 v95, 0, v95
	v_max_f32_e32 v88, 0, v88
	v_max_f32_e32 v89, 0, v89
	v_max_f32_e32 v90, 0, v90
	v_max_f32_e32 v91, 0, v91
	v_pk_mul_f32 v[92:93], v[92:93], v[92:93]
	v_pk_mul_f32 v[94:95], v[94:95], v[94:95]
	v_pk_mul_f32 v[88:89], v[88:89], v[88:89]
	v_pk_mul_f32 v[90:91], v[90:91], v[90:91]
	v_cvt_pk_bf16_f32 v152, v92, v93
	v_cvt_pk_bf16_f32 v153, v94, v95
	v_cvt_pk_bf16_f32 v154, v88, v89
	v_cvt_pk_bf16_f32 v155, v90, v91
	ds_write_b128 v145, v[152:155]
	ds_read_b128 v[160:163], v146
	s_waitcnt lgkmcnt(2)
	global_store_dwordx4 v147, v[172:175], s[16:17] offset:256 nt
	v_max_f32_e32 v84, 0, v84
	v_max_f32_e32 v85, 0, v85
	v_max_f32_e32 v86, 0, v86
	v_max_f32_e32 v87, 0, v87
	v_max_f32_e32 v80, 0, v80
	v_max_f32_e32 v81, 0, v81
	v_max_f32_e32 v82, 0, v82
	v_max_f32_e32 v83, 0, v83
	v_pk_mul_f32 v[84:85], v[84:85], v[84:85]
	v_pk_mul_f32 v[86:87], v[86:87], v[86:87]
	v_pk_mul_f32 v[80:81], v[80:81], v[80:81]
	v_pk_mul_f32 v[82:83], v[82:83], v[82:83]
	v_cvt_pk_bf16_f32 v156, v84, v85
	v_cvt_pk_bf16_f32 v157, v86, v87
	v_cvt_pk_bf16_f32 v158, v80, v81
	v_cvt_pk_bf16_f32 v159, v82, v83
	ds_write_b128 v145, v[156:159] offset:8192
	ds_read_b128 v[164:167], v146 offset:8192
	s_waitcnt lgkmcnt(2)
	s_add_u32 s16, s16, 0x20000
	s_addc_u32 s17, s17, 0
	global_store_dwordx4 v147, v[160:163], s[16:17] nt
	v_max_f32_e32 v76, 0, v76
	v_max_f32_e32 v77, 0, v77
	v_max_f32_e32 v78, 0, v78
	v_max_f32_e32 v79, 0, v79
	v_max_f32_e32 v72, 0, v72
	v_max_f32_e32 v73, 0, v73
	v_max_f32_e32 v74, 0, v74
	v_max_f32_e32 v75, 0, v75
	v_pk_mul_f32 v[76:77], v[76:77], v[76:77]
	v_pk_mul_f32 v[78:79], v[78:79], v[78:79]
	v_pk_mul_f32 v[72:73], v[72:73], v[72:73]
	v_pk_mul_f32 v[74:75], v[74:75], v[74:75]
	v_cvt_pk_bf16_f32 v152, v76, v77
	v_cvt_pk_bf16_f32 v153, v78, v79
	v_cvt_pk_bf16_f32 v154, v72, v73
	v_cvt_pk_bf16_f32 v155, v74, v75
	ds_write_b128 v145, v[152:155]
	ds_read_b128 v[168:171], v146
	s_waitcnt lgkmcnt(2)
; DI unsigned pk2(float lo, float hi) { f32x2 v = {lo, hi}; bf2_t r = __builtin_convertvector(v, bf2_t); return __builtin_bit_cast(unsigned, r); }
; #define PG8_BAR __builtin_amdgcn_s_barrier()
; template <class Epi>
; DI void gemm_phase(LAS unsigned char* lds, const Gemm g, const Order& S, const Epi& E, const int wv) {
;     ...
;         if (!has_next) break;
; #pragma unroll
;         for (int a = 0; a < 2; ++a)
; #pragma unroll
;             for (int b = 0; b < 2; ++b)
; #pragma unroll
;                 for (int m = 0; m < 4; ++m)
; #pragma unroll
;                     for (int n = 0; n < 2; ++n) acc[a][b][m][n] = (f32x4){0.f, 0.f, 0.f, 0.f};
;         cur = nxt; cA = nA; cB = nB; ++ui;
;         if (wr == 1) PG8_BAR;
;     DI void operator()(const f32x4 (&acc)[2][2][4][2], const Unit& u, int wr, int wc, int fr, int fq) const {
;     ...
;             for (int m = 0; m < 4; ++m) { const size_t row = (size_t)(row0 + ai * HALF + m * 16);
; #pragma unroll
;                 for (int bj = 0; bj < 2; ++bj) { const int col = col0 + bj * HALF; f32x4 v0 = acc[ai][bj][m][0], v1 = acc[ai][bj][m][1];
; #pragma unroll
;                     for (int j = 0; j < 4; ++j) { const float a = fmaxf(v0[j], 0.f), b = fmaxf(v1[j], 0.f); v0[j] = a * a; v1[j] = b * b; }
;                     u32x4 w; w.x = pk2(v0[0], v0[1]); w.y = pk2(v0[2], v0[3]); w.z = pk2(v1[0], v1[1]); w.w = pk2(v1[2], v1[3]);
;                     *(u32x4*)(U + row * FF + col) = w; } }
	global_store_dwordx4 v147, v[164:167], s[16:17] offset:256 nt
	v_max_f32_e32 v68, 0, v68
	v_max_f32_e32 v69, 0, v69
	v_max_f32_e32 v70, 0, v70
	v_max_f32_e32 v71, 0, v71
	v_max_f32_e32 v64, 0, v64
	v_max_f32_e32 v65, 0, v65
	v_max_f32_e32 v66, 0, v66
	v_max_f32_e32 v67, 0, v67
	v_pk_mul_f32 v[68:69], v[68:69], v[68:69]
	v_pk_mul_f32 v[70:71], v[70:71], v[70:71]
	v_pk_mul_f32 v[64:65], v[64:65], v[64:65]
	v_pk_mul_f32 v[66:67], v[66:67], v[66:67]
	v_cvt_pk_bf16_f32 v156, v68, v69
	v_cvt_pk_bf16_f32 v157, v70, v71
	v_cvt_pk_bf16_f32 v158, v64, v65
	v_cvt_pk_bf16_f32 v159, v66, v67
	ds_write_b128 v145, v[156:159] offset:8192
	ds_read_b128 v[172:175], v146 offset:8192
	s_waitcnt lgkmcnt(2)
	s_add_u32 s16, s16, 0x20000
	s_addc_u32 s17, s17, 0
	global_store_dwordx4 v147, v[168:171], s[16:17] nt
	v_max_f32_e32 v60, 0, v60
	v_max_f32_e32 v61, 0, v61
	v_max_f32_e32 v62, 0, v62
	v_max_f32_e32 v63, 0, v63
	v_max_f32_e32 v56, 0, v56
	v_max_f32_e32 v57, 0, v57
	v_max_f32_e32 v58, 0, v58
	v_max_f32_e32 v59, 0, v59
	v_pk_mul_f32 v[60:61], v[60:61], v[60:61]
	v_pk_mul_f32 v[62:63], v[62:63], v[62:63]
	v_pk_mul_f32 v[56:57], v[56:57], v[56:57]
	v_pk_mul_f32 v[58:59], v[58:59], v[58:59]
	v_cvt_pk_bf16_f32 v152, v60, v61
	v_cvt_pk_bf16_f32 v153, v62, v63
	v_cvt_pk_bf16_f32 v154, v56, v57
	v_cvt_pk_bf16_f32 v155, v58, v59
	ds_write_b128 v145, v[152:155]
	ds_read_b128 v[160:163], v146
	s_waitcnt lgkmcnt(2)
	global_store_dwordx4 v147, v[172:175], s[16:17] offset:256 nt
	v_max_f32_e32 v52, 0, v52
	v_max_f32_e32 v53, 0, v53
	v_max_f32_e32 v54, 0, v54
	v_max_f32_e32 v55, 0, v55
	v_max_f32_e32 v48, 0, v48
	v_max_f32_e32 v49, 0, v49
	v_max_f32_e32 v50, 0, v50
	v_max_f32_e32 v51, 0, v51
	v_pk_mul_f32 v[52:53], v[52:53], v[52:53]
	v_pk_mul_f32 v[54:55], v[54:55], v[54:55]
	v_pk_mul_f32 v[48:49], v[48:49], v[48:49]
	v_pk_mul_f32 v[50:51], v[50:51], v[50:51]
	v_cvt_pk_bf16_f32 v156, v52, v53
	v_cvt_pk_bf16_f32 v157, v54, v55
	v_cvt_pk_bf16_f32 v158, v48, v49
	v_cvt_pk_bf16_f32 v159, v50, v51
	ds_write_b128 v145, v[156:159] offset:8192
	ds_read_b128 v[164:167], v146 offset:8192
	s_waitcnt lgkmcnt(2)
	s_add_u32 s16, s16, 0xa0000
	s_addc_u32 s17, s17, 0
	global_store_dwordx4 v147, v[160:163], s[16:17] nt
	v_max_f32_e32 v44, 0, v44
	v_max_f32_e32 v45, 0, v45
	v_max_f32_e32 v46, 0, v46
	v_max_f32_e32 v47, 0, v47
	v_max_f32_e32 v40, 0, v40
	v_max_f32_e32 v41, 0, v41
	v_max_f32_e32 v42, 0, v42
	v_max_f32_e32 v43, 0, v43
	v_pk_mul_f32 v[44:45], v[44:45], v[44:45]
	v_pk_mul_f32 v[46:47], v[46:47], v[46:47]
	v_pk_mul_f32 v[40:41], v[40:41], v[40:41]
	v_pk_mul_f32 v[42:43], v[42:43], v[42:43]
	v_cvt_pk_bf16_f32 v152, v44, v45
	v_cvt_pk_bf16_f32 v153, v46, v47
	v_cvt_pk_bf16_f32 v154, v40, v41
	v_cvt_pk_bf16_f32 v155, v42, v43
	ds_write_b128 v145, v[152:155]
	ds_read_b128 v[168:171], v146
	s_waitcnt lgkmcnt(2)
	global_store_dwordx4 v147, v[164:167], s[16:17] offset:256 nt
	v_max_f32_e32 v36, 0, v36
	v_max_f32_e32 v37, 0, v37
	v_max_f32_e32 v38, 0, v38
	v_max_f32_e32 v39, 0, v39
	v_max_f32_e32 v32, 0, v32
	v_max_f32_e32 v33, 0, v33
	v_max_f32_e32 v34, 0, v34
	v_max_f32_e32 v35, 0, v35
	v_pk_mul_f32 v[36:37], v[36:37], v[36:37]
	v_pk_mul_f32 v[38:39], v[38:39], v[38:39]
	v_pk_mul_f32 v[32:33], v[32:33], v[32:33]
	v_pk_mul_f32 v[34:35], v[34:35], v[34:35]
	v_cvt_pk_bf16_f32 v156, v36, v37
	v_cvt_pk_bf16_f32 v157, v38, v39
	v_cvt_pk_bf16_f32 v158, v32, v33
	v_cvt_pk_bf16_f32 v159, v34, v35
	ds_write_b128 v145, v[156:159] offset:8192
	ds_read_b128 v[172:175], v146 offset:8192
	s_waitcnt lgkmcnt(2)
	s_add_u32 s16, s16, 0x20000
	s_addc_u32 s17, s17, 0
	global_store_dwordx4 v147, v[168:171], s[16:17] nt
	v_max_f32_e32 v28, 0, v28
	v_max_f32_e32 v29, 0, v29
	v_max_f32_e32 v30, 0, v30
	v_max_f32_e32 v31, 0, v31
	v_max_f32_e32 v24, 0, v24
	v_max_f32_e32 v25, 0, v25
	v_max_f32_e32 v26, 0, v26
	v_max_f32_e32 v27, 0, v27
	v_pk_mul_f32 v[28:29], v[28:29], v[28:29]
	v_pk_mul_f32 v[30:31], v[30:31], v[30:31]
	v_pk_mul_f32 v[24:25], v[24:25], v[24:25]
	v_pk_mul_f32 v[26:27], v[26:27], v[26:27]
	v_cvt_pk_bf16_f32 v152, v28, v29
	v_cvt_pk_bf16_f32 v153, v30, v31
	v_cvt_pk_bf16_f32 v154, v24, v25
	v_cvt_pk_bf16_f32 v155, v26, v27
	ds_write_b128 v145, v[152:155]
	ds_read_b128 v[160:163], v146
	s_waitcnt lgkmcnt(2)
	global_store_dwordx4 v147, v[172:175], s[16:17] offset:256 nt
	v_max_f32_e32 v20, 0, v20
	v_max_f32_e32 v21, 0, v21
	v_max_f32_e32 v22, 0, v22
	v_max_f32_e32 v23, 0, v23
	v_max_f32_e32 v16, 0, v16
	v_max_f32_e32 v17, 0, v17
	v_max_f32_e32 v18, 0, v18
	v_max_f32_e32 v19, 0, v19
	v_pk_mul_f32 v[20:21], v[20:21], v[20:21]
	v_pk_mul_f32 v[22:23], v[22:23], v[22:23]
	v_pk_mul_f32 v[16:17], v[16:17], v[16:17]
	v_pk_mul_f32 v[18:19], v[18:19], v[18:19]
	v_cvt_pk_bf16_f32 v156, v20, v21
	v_cvt_pk_bf16_f32 v157, v22, v23
	v_cvt_pk_bf16_f32 v158, v16, v17
	v_cvt_pk_bf16_f32 v159, v18, v19
	ds_write_b128 v145, v[156:159] offset:8192
	ds_read_b128 v[164:167], v146 offset:8192
	s_waitcnt lgkmcnt(2)
	s_add_u32 s16, s16, 0x20000
	s_addc_u32 s17, s17, 0
	global_store_dwordx4 v147, v[160:163], s[16:17] nt
	v_max_f32_e32 v12, 0, v12
	v_max_f32_e32 v13, 0, v13
	v_max_f32_e32 v14, 0, v14
	v_max_f32_e32 v15, 0, v15
	v_max_f32_e32 v8, 0, v8
	v_max_f32_e32 v9, 0, v9
	v_max_f32_e32 v10, 0, v10
	v_max_f32_e32 v11, 0, v11
	v_pk_mul_f32 v[12:13], v[12:13], v[12:13]
	v_pk_mul_f32 v[14:15], v[14:15], v[14:15]
	v_pk_mul_f32 v[8:9], v[8:9], v[8:9]
	v_pk_mul_f32 v[10:11], v[10:11], v[10:11]
	v_cvt_pk_bf16_f32 v152, v12, v13
	v_cvt_pk_bf16_f32 v153, v14, v15
	v_cvt_pk_bf16_f32 v154, v8, v9
	v_cvt_pk_bf16_f32 v155, v10, v11
	ds_write_b128 v145, v[152:155]
	ds_read_b128 v[168:171], v146
	s_waitcnt lgkmcnt(2)
	global_store_dwordx4 v147, v[164:167], s[16:17] offset:256 nt
	v_max_f32_e32 v4, 0, v4
	v_max_f32_e32 v5, 0, v5
	v_max_f32_e32 v6, 0, v6
	v_max_f32_e32 v7, 0, v7
	v_max_f32_e32 v0, 0, v0
	v_max_f32_e32 v1, 0, v1
	v_max_f32_e32 v2, 0, v2
	v_max_f32_e32 v3, 0, v3
	v_pk_mul_f32 v[4:5], v[4:5], v[4:5]
	v_pk_mul_f32 v[6:7], v[6:7], v[6:7]
	v_pk_mul_f32 v[0:1], v[0:1], v[0:1]
	v_pk_mul_f32 v[2:3], v[2:3], v[2:3]
	v_cvt_pk_bf16_f32 v156, v4, v5
	v_cvt_pk_bf16_f32 v157, v6, v7
	v_cvt_pk_bf16_f32 v158, v0, v1
	v_cvt_pk_bf16_f32 v159, v2, v3
	ds_write_b128 v145, v[156:159] offset:8192
	ds_read_b128 v[172:175], v146 offset:8192
	s_waitcnt lgkmcnt(2)
	s_add_u32 s16, s16, 0x20000
	s_addc_u32 s17, s17, 0
	global_store_dwordx4 v147, v[168:171], s[16:17] nt
	s_waitcnt lgkmcnt(0)
	global_store_dwordx4 v147, v[172:175], s[16:17] offset:256 nt
	s_andn2_b64 vcc, exec, s[4:5]
	s_mov_b64 s[4:5], -1
	s_movk_i32 s36, 0x44
	s_cbranch_vccnz .LBB0_903
	v_readlane_b32 s4, v254, 58
	v_readlane_b32 s5, v254, 59
	s_and_b64 vcc, exec, s[4:5]
	s_cbranch_vccnz .LBB0_902
	s_barrier
	s_branch .LBB0_902
